# v15: next-item tile prefetch with exact vmcnt waits (gate wait no longer drains the prefetch)
# baseline (speedup 1.0000x reference)
; __device__ __forceinline__ unsigned cvtpk(float lo, float hi) { f32x2 v = {lo, hi}; bf16x2_t b = __builtin_convertvector(v, bf16x2_t); return *(unsigned*)&b; }
; __device__ __forceinline__ float lo16(unsigned w) { return __uint_as_float(w << 16); }
; __device__ __forceinline__ float hi16(unsigned w) { return __uint_as_float(w & 0xffff0000u); }
; #define SWAIT() asm volatile("s_waitcnt vmcnt(3)" ::: "memory")
; __device__ void phase_attn(const Params& p, char* lds) {
;     ...
;   for (int it = slot; it < nitems / 8; it += per) {
;     const int pair = (it >> 5) * 8 + xcd, qblk = it & 31;
;     const int b = pair >> 4, h = pair & 15;
;     const size_t row0 = (size_t)b * TL;
;     const size_t qrow = row0 + qblk * 256 + wid * 32 + r32;
;     const bf16_t* Kh = KVg + row0 * 2048 + h * 128;
;     const bf16_t* Kp = KPg + row0 * 32;
;     float m_reg = 0.f, l_reg = 0.f;
;     f32x16 o[2];
; #pragma unroll
;     for (int dd = 0; dd < 2; ++dd)
; #pragma unroll
;       for (int r = 0; r < 16; ++r) o[dd][r] = 0.f;
;     bf16x8 qr[6];
;     {
;       const bf16_t* Qw = Qg + qrow * 1536 + h * 96 + hi * 8;
; #pragma unroll
;       for (int d0 = 0; d0 < 6; ++d0) qr[d0] = *(const bf16x8*)(Qw + d0 * 16);
;       const int t = qblk * 256 + wid * 32 + r32;
;       const f32x2* tb = rope + (hi ? (t & 63) : (t >> 6)) * 8;
;       const u32x4 x1 = *(const u32x4*)&qr[4], x2 = *(const u32x4*)&qr[5];
;       u32x4 n1, n2;
; #pragma unroll
;       for (int q = 0; q < 4; ++q) {
;         const f32x2 csA = tb[2 * q], csB = tb[2 * q + 1];
;         const float a0 = lo16(x1[q]), a1 = hi16(x1[q]), b0 = lo16(x2[q]), b1 = hi16(x2[q]);
;         n1[q] = cvtpk(a0 * csA[0] - b0 * csA[1], a1 * csB[0] - b1 * csB[1]);
;         n2[q] = cvtpk(a0 * csA[1] + b0 * csA[0], a1 * csB[1] + b1 * csB[0]);
;       }
;       qr[4] = *(bf16x8*)&n1; qr[5] = *(bf16x8*)&n2;
;     }
;     struct { bf16x8 vs, ks, ps; } sr_[2];
;     ...
;     f32x16 pA0, pA1, pB0, pB1; float alA, alB; bf16x8 pa0, pa1, pa2, pa3;
;     constexpr int NT = TL / 64;
;     SLOAD(0, 0); asm volatile("s_waitcnt vmcnt(0)" ::: "memory"); SWRITE(0, 0); __syncthreads();
;     at_qkt(pA0, pA1, K_lds, qr, r32, hi, 0.f); at_partialSM(pA0, pA1, m_reg, alA, true);
;     SLOAD(1, 64); SLOAD(0, 128);
;     SWAIT(); SWRITE(1, 1); __syncthreads();
.Lat_item:
	s_lshr_b32 s16, s12, 5
	s_lshl_b32 s16, s16, 3
	s_add_i32 s16, s16, s43
	s_and_b32 s20, s12, 31
	s_lshr_b32 s22, s16, 4
	s_and_b32 s21, s16, 15
	s_mul_i32 s17, s22, 0x2100
	s_lshl_b32 s18, s20, 8
	s_add_i32 s17, s17, s18
	s_mul_i32 s18, s17, 0xc00
	s_mul_i32 s19, s21, 0xc0
	s_add_i32 s18, s18, s19
	s_add_u32 s18, s18, 0x8400000
	s_add_u32 s10, s86, s18
	s_addc_u32 s11, s87, 0
	s_lshl_b32 s18, s17, 11
	s_lshl_b32 s19, s21, 7
	s_add_i32 s18, s18, s19
	s_add_u32 s18, s18, 0x21000000
	s_add_u32 s28, s86, s18
	s_addc_u32 s29, s87, 0
	global_load_dwordx4 v[80:83], v234, s[10:11] offset:0
	global_load_dwordx4 v[84:87], v234, s[10:11] offset:32
	global_load_dwordx4 v[88:91], v234, s[10:11] offset:64
	global_load_dwordx4 v[92:95], v234, s[10:11] offset:96
	global_load_dwordx4 v[96:99], v234, s[10:11] offset:128
	global_load_dwordx4 v[100:103], v234, s[10:11] offset:160
	s_and_b32 s16, s14, 1
	s_lshl_b32 s16, s16, 5
	v_and_b32_e32 v183, 31, v178
	v_add_u32_e32 v183, s16, v183
	v_lshlrev_b32_e32 v183, 6, v183
	s_lshl_b32 s16, s20, 2
	s_lshr_b32 s17, s14, 1
	s_add_i32 s16, s16, s17
	s_lshl_b32 s16, s16, 6
	v_mov_b32_e32 v228, s16
	v_and_b32_e32 v229, 32, v178
	v_cmp_ne_u32_e32 vcc, 0, v229
	s_nop 1
	v_cndmask_b32_e32 v183, v228, v183, vcc
	global_load_dwordx4 v[200:203], v183, s[34:35] offset:0
	global_load_dwordx4 v[204:207], v183, s[34:35] offset:16
	global_load_dwordx4 v[208:211], v183, s[34:35] offset:32
	global_load_dwordx4 v[212:215], v183, s[34:35] offset:48
	s_barrier
	s_waitcnt vmcnt(42)
	ds_write_b128 v167, v[32:35] offset:0
	ds_write_b128 v131, v[36:39] offset:0
	ds_write_b128 v169, v[40:43] offset:0
	ds_write_b128 v167, v[44:47] offset:13312
	ds_write_b128 v131, v[48:51] offset:16384
	ds_write_b128 v169, v[52:55] offset:13312
	s_waitcnt lgkmcnt(0)
	global_load_dwordx4 v[120:123], v129, s[4:5]
	global_load_dwordx4 v[124:127], v129, s[4:5] offset:128
	global_load_dwordx4 v[132:135], v130, s[6:7]
	s_add_u32 s4, s4, 0x40000
	s_addc_u32 s5, s5, 0
	s_add_u32 s6, s6, 0x1000
	s_addc_u32 s7, s7, 0
	s_waitcnt vmcnt(3)
	v_lshlrev_b32_e32 v175, 16, v96
	v_and_b32_e32 v183, 0xffff0000, v96
	v_lshlrev_b32_e32 v228, 16, v100
	v_and_b32_e32 v229, 0xffff0000, v100
	v_mul_f32_e32 v230, v228, v201
	v_mul_f32_e32 v174, v229, v203
	v_fma_f32 v230, v175, v200, -v230
	v_fma_f32 v174, v183, v202, -v174
	v_mul_f32_e32 v175, v175, v201
	v_mul_f32_e32 v183, v183, v203
	v_fma_f32 v175, v228, v200, v175
	v_fma_f32 v183, v229, v202, v183
	v_cvt_pk_bf16_f32 v96, v230, v174
	v_cvt_pk_bf16_f32 v100, v175, v183
	v_lshlrev_b32_e32 v175, 16, v97
	v_and_b32_e32 v183, 0xffff0000, v97
	v_lshlrev_b32_e32 v228, 16, v101
	v_and_b32_e32 v229, 0xffff0000, v101
	v_mul_f32_e32 v230, v228, v205
	v_mul_f32_e32 v174, v229, v207
	v_fma_f32 v230, v175, v204, -v230
	v_fma_f32 v174, v183, v206, -v174
	v_mul_f32_e32 v175, v175, v205
	v_mul_f32_e32 v183, v183, v207
	v_fma_f32 v175, v228, v204, v175
	v_fma_f32 v183, v229, v206, v183
	v_cvt_pk_bf16_f32 v97, v230, v174
	v_cvt_pk_bf16_f32 v101, v175, v183
	v_lshlrev_b32_e32 v175, 16, v98
	v_and_b32_e32 v183, 0xffff0000, v98
	v_lshlrev_b32_e32 v228, 16, v102
	v_and_b32_e32 v229, 0xffff0000, v102
	v_mul_f32_e32 v230, v228, v209
	v_mul_f32_e32 v174, v229, v211
	v_fma_f32 v230, v175, v208, -v230
	v_fma_f32 v174, v183, v210, -v174
	v_mul_f32_e32 v175, v175, v209
	v_mul_f32_e32 v183, v183, v211
	v_fma_f32 v175, v228, v208, v175
	v_fma_f32 v183, v229, v210, v183
	v_cvt_pk_bf16_f32 v98, v230, v174
	v_cvt_pk_bf16_f32 v102, v175, v183
	v_lshlrev_b32_e32 v175, 16, v99
	v_and_b32_e32 v183, 0xffff0000, v99
	v_lshlrev_b32_e32 v228, 16, v103
	v_and_b32_e32 v229, 0xffff0000, v103
	v_mul_f32_e32 v230, v228, v213
	v_mul_f32_e32 v174, v229, v215
	v_fma_f32 v230, v175, v212, -v230
	v_fma_f32 v174, v183, v214, -v174
	v_mul_f32_e32 v175, v175, v213
	v_mul_f32_e32 v183, v183, v215
	v_fma_f32 v175, v228, v212, v175
	v_fma_f32 v183, v229, v214, v183
	v_cvt_pk_bf16_f32 v99, v230, v174
	v_cvt_pk_bf16_f32 v103, v175, v183
	v_mov_b32_e32 v0, 0
	v_mov_b32_e32 v1, 0
	v_mov_b32_e32 v2, 0
	v_mov_b32_e32 v3, 0
	v_mov_b32_e32 v4, 0
	v_mov_b32_e32 v5, 0
	v_mov_b32_e32 v6, 0
	v_mov_b32_e32 v7, 0
	v_mov_b32_e32 v8, 0
	v_mov_b32_e32 v9, 0
	v_mov_b32_e32 v10, 0
	v_mov_b32_e32 v11, 0
	v_mov_b32_e32 v12, 0
	v_mov_b32_e32 v13, 0
	v_mov_b32_e32 v14, 0
	v_mov_b32_e32 v15, 0
	v_mov_b32_e32 v16, 0
	v_mov_b32_e32 v17, 0
	v_mov_b32_e32 v18, 0
	v_mov_b32_e32 v19, 0
	v_mov_b32_e32 v20, 0
	v_mov_b32_e32 v21, 0
	v_mov_b32_e32 v22, 0
	v_mov_b32_e32 v23, 0
	v_mov_b32_e32 v24, 0
	v_mov_b32_e32 v25, 0
	v_mov_b32_e32 v26, 0
	v_mov_b32_e32 v27, 0
	v_mov_b32_e32 v28, 0
	v_mov_b32_e32 v29, 0
	v_mov_b32_e32 v30, 0
	v_mov_b32_e32 v31, 0
	v_mov_b32_e32 v173, 0
	s_barrier
	ds_read_b128 v[184:187], v170 offset:0
	ds_read_b128 v[188:191], v170 offset:6656
	ds_read_b128 v[192:195], v170 offset:32
	ds_read_b128 v[196:199], v170 offset:6688
	s_cmp_eq_u32 s15, 0
	s_cbranch_scc1 .Lat_nostag
	s_barrier

; __device__ __forceinline__ float bf2f(bf16_t u) { return __uint_as_float(((unsigned)u) << 16); }
; __device__ __forceinline__ bf16_t f2bf(float f) { return (bf16_t)(cvtpk(f, 0.f) & 0xffffu); }
; __device__ __forceinline__ int crow(int r, int hi) { return (r & 3) + 8 * (r >> 2) + 4 * hi; }
; __device__ __forceinline__ float sigmoidf_(float x) { return __builtin_amdgcn_rcpf(1.f + __expf(-x)); }
; __device__ void phase_attn(const Params& p, char* lds) {
;     ...
;     if (hi == 0) li_l[r32] = l_reg;
;     asm volatile("s_waitcnt lgkmcnt(0)" ::: "memory");
;     float rli[16];
; #pragma unroll
;     for (int r = 0; r < 16; ++r) rli[r] = __builtin_amdgcn_rcpf(li_l[crow(r, hi)]);
;     bf16_t* Gw = G1 + (row0 + qblk * 256 + wid * 32) * 1024 + h * 64 + r32;
;     bf16_t gin[32];
; #pragma unroll
;     for (int r = 0; r < 16; ++r) { gin[2 * r] = Gw[(size_t)crow(r, hi) * 1024]; gin[2 * r + 1] = Gw[(size_t)crow(r, hi) * 1024 + 32]; }
;     asm volatile("" ::: "memory");
; #pragma unroll
;     for (int r = 0; r < 16; ++r) {
;       const int orow = crow(r, hi);
; #pragma unroll
;       for (int d0 = 0; d0 < 2; ++d0) {
;         const float gt = bf2f(gin[2 * r + d0]);
;         Gw[(size_t)orow * 1024 + d0 * 32] = f2bf(o[d0][r] * rli[r] * gt * sigmoidf_(gt));
;       }
;     }
.Lat_nobal:
	v_mov_b32_e32 v175, v173
	s_nop 1
	v_permlane32_swap_b32_e32 v173, v175
	v_add_f32_e32 v173, v173, v175
	ds_write_b32 v244, v173 offset:128
	s_waitcnt lgkmcnt(0)
	ds_read_b128 v[184:187], v245 offset:128
	ds_read_b128 v[188:191], v245 offset:160
	ds_read_b128 v[192:195], v245 offset:192
	ds_read_b128 v[196:199], v245 offset:224
	s_waitcnt lgkmcnt(0)
	v_rcp_f32_e32 v184, v184
	v_rcp_f32_e32 v185, v185
	v_rcp_f32_e32 v186, v186
	v_rcp_f32_e32 v187, v187
	v_rcp_f32_e32 v188, v188
	v_rcp_f32_e32 v189, v189
	v_rcp_f32_e32 v190, v190
	v_rcp_f32_e32 v191, v191
	v_rcp_f32_e32 v192, v192
	v_rcp_f32_e32 v193, v193
	v_rcp_f32_e32 v194, v194
	v_rcp_f32_e32 v195, v195
	v_rcp_f32_e32 v196, v196
	v_rcp_f32_e32 v197, v197
	v_rcp_f32_e32 v198, v198
	v_rcp_f32_e32 v199, v199
	v_mul_f32_e32 v0, v0, v184
	v_mul_f32_e32 v16, v16, v184
	v_mul_f32_e32 v1, v1, v185
	v_mul_f32_e32 v17, v17, v185
	v_mul_f32_e32 v2, v2, v186
	v_mul_f32_e32 v18, v18, v186
	v_mul_f32_e32 v3, v3, v187
	v_mul_f32_e32 v19, v19, v187
	v_mul_f32_e32 v4, v4, v188
	v_mul_f32_e32 v20, v20, v188
	v_mul_f32_e32 v5, v5, v189
	v_mul_f32_e32 v21, v21, v189
	v_mul_f32_e32 v6, v6, v190
	v_mul_f32_e32 v22, v22, v190
	v_mul_f32_e32 v7, v7, v191
	v_mul_f32_e32 v23, v23, v191
	v_mul_f32_e32 v8, v8, v192
	v_mul_f32_e32 v24, v24, v192
	v_mul_f32_e32 v9, v9, v193
	v_mul_f32_e32 v25, v25, v193
	v_mul_f32_e32 v10, v10, v194
	v_mul_f32_e32 v26, v26, v194
	v_mul_f32_e32 v11, v11, v195
	v_mul_f32_e32 v27, v27, v195
	v_mul_f32_e32 v12, v12, v196
	v_mul_f32_e32 v28, v28, v196
	v_mul_f32_e32 v13, v13, v197
	v_mul_f32_e32 v29, v29, v197
	v_mul_f32_e32 v14, v14, v198
	v_mul_f32_e32 v30, v30, v198
	v_mul_f32_e32 v15, v15, v199
	v_mul_f32_e32 v31, v31, v199
	s_waitcnt vmcnt(6)
	v_lshlrev_b32_e32 v120, 16, v120
	v_lshlrev_b32_e32 v121, 16, v121
	v_lshlrev_b32_e32 v122, 16, v122
	v_lshlrev_b32_e32 v123, 16, v123
	v_lshlrev_b32_e32 v124, 16, v124
	v_lshlrev_b32_e32 v125, 16, v125
	v_lshlrev_b32_e32 v126, 16, v126
	v_lshlrev_b32_e32 v127, 16, v127
	v_mul_f32_e32 v64, 0xbfb8aa3b, v120
	v_mul_f32_e32 v65, 0xbfb8aa3b, v121
	v_mul_f32_e32 v66, 0xbfb8aa3b, v122
	v_mul_f32_e32 v67, 0xbfb8aa3b, v123
	v_mul_f32_e32 v68, 0xbfb8aa3b, v124
	v_mul_f32_e32 v69, 0xbfb8aa3b, v125
	v_mul_f32_e32 v70, 0xbfb8aa3b, v126
	v_mul_f32_e32 v71, 0xbfb8aa3b, v127
	v_exp_f32_e32 v64, v64
	v_exp_f32_e32 v65, v65
	v_exp_f32_e32 v66, v66
	v_exp_f32_e32 v67, v67
	v_exp_f32_e32 v68, v68
	v_exp_f32_e32 v69, v69
	v_exp_f32_e32 v70, v70
	v_exp_f32_e32 v71, v71
	v_add_f32_e32 v64, 1.0, v64
	v_add_f32_e32 v65, 1.0, v65
	v_add_f32_e32 v66, 1.0, v66
	v_add_f32_e32 v67, 1.0, v67
	v_add_f32_e32 v68, 1.0, v68
	v_add_f32_e32 v69, 1.0, v69
	v_add_f32_e32 v70, 1.0, v70
	v_add_f32_e32 v71, 1.0, v71
	v_rcp_f32_e32 v64, v64
	v_rcp_f32_e32 v65, v65
	v_rcp_f32_e32 v66, v66
	v_rcp_f32_e32 v67, v67
	v_rcp_f32_e32 v68, v68
	v_rcp_f32_e32 v69, v69
	v_rcp_f32_e32 v70, v70
	v_rcp_f32_e32 v71, v71
	v_mul_f32_e32 v0, v0, v120
	v_mul_f32_e32 v16, v16, v121
	v_mul_f32_e32 v1, v1, v122
	v_mul_f32_e32 v17, v17, v123
	v_mul_f32_e32 v2, v2, v124
	v_mul_f32_e32 v18, v18, v125
	v_mul_f32_e32 v3, v3, v126
	v_mul_f32_e32 v19, v19, v127
	v_mul_f32_e32 v0, v0, v64
	v_mul_f32_e32 v16, v16, v65
	v_mul_f32_e32 v1, v1, v66
	v_mul_f32_e32 v17, v17, v67
	v_mul_f32_e32 v2, v2, v68
	v_mul_f32_e32 v18, v18, v69
	v_mul_f32_e32 v3, v3, v70
	v_mul_f32_e32 v19, v19, v71
	v_cvt_pk_bf16_f32 v0, v0, v0
	v_cvt_pk_bf16_f32 v16, v16, v16
	v_cvt_pk_bf16_f32 v1, v1, v1
	v_cvt_pk_bf16_f32 v17, v17, v17
	v_cvt_pk_bf16_f32 v2, v2, v2
	v_cvt_pk_bf16_f32 v18, v18, v18
	v_cvt_pk_bf16_f32 v3, v3, v3
	v_cvt_pk_bf16_f32 v19, v19, v19
	s_add_u32 s8, s28, 0x0
	s_addc_u32 s9, s29, 0
	global_store_short v235, v0, s[8:9] offset:0
	global_store_short v235, v16, s[8:9] offset:64
	global_store_short v235, v1, s[8:9] offset:2048
	global_store_short v235, v17, s[8:9] offset:2112
	s_add_u32 s8, s28, 0x1000
	s_addc_u32 s9, s29, 0
	global_store_short v235, v2, s[8:9] offset:0
	global_store_short v235, v18, s[8:9] offset:64
	global_store_short v235, v3, s[8:9] offset:2048
	global_store_short v235, v19, s[8:9] offset:2112
	v_lshlrev_b32_e32 v132, 16, v132
	v_lshlrev_b32_e32 v133, 16, v133
	v_lshlrev_b32_e32 v134, 16, v134
	v_lshlrev_b32_e32 v135, 16, v135
	v_lshlrev_b32_e32 v136, 16, v136
	v_lshlrev_b32_e32 v137, 16, v137
	v_lshlrev_b32_e32 v138, 16, v138
	v_lshlrev_b32_e32 v139, 16, v139
	v_mul_f32_e32 v64, 0xbfb8aa3b, v132
	v_mul_f32_e32 v65, 0xbfb8aa3b, v133
	v_mul_f32_e32 v66, 0xbfb8aa3b, v134
	v_mul_f32_e32 v67, 0xbfb8aa3b, v135
	v_mul_f32_e32 v68, 0xbfb8aa3b, v136
	v_mul_f32_e32 v69, 0xbfb8aa3b, v137
	v_mul_f32_e32 v70, 0xbfb8aa3b, v138
	v_mul_f32_e32 v71, 0xbfb8aa3b, v139
	v_exp_f32_e32 v64, v64
	v_exp_f32_e32 v65, v65
	v_exp_f32_e32 v66, v66
	v_exp_f32_e32 v67, v67
	v_exp_f32_e32 v68, v68
	v_exp_f32_e32 v69, v69
	v_exp_f32_e32 v70, v70
	v_exp_f32_e32 v71, v71
	v_add_f32_e32 v64, 1.0, v64
	v_add_f32_e32 v65, 1.0, v65
	v_add_f32_e32 v66, 1.0, v66
	v_add_f32_e32 v67, 1.0, v67
	v_add_f32_e32 v68, 1.0, v68
	v_add_f32_e32 v69, 1.0, v69
	v_add_f32_e32 v70, 1.0, v70
	v_add_f32_e32 v71, 1.0, v71
	v_rcp_f32_e32 v64, v64
	v_rcp_f32_e32 v65, v65
	v_rcp_f32_e32 v66, v66
	v_rcp_f32_e32 v67, v67
	v_rcp_f32_e32 v68, v68
	v_rcp_f32_e32 v69, v69
	v_rcp_f32_e32 v70, v70
	v_rcp_f32_e32 v71, v71
	v_mul_f32_e32 v4, v4, v132
	v_mul_f32_e32 v20, v20, v133
	v_mul_f32_e32 v5, v5, v134
	v_mul_f32_e32 v21, v21, v135
	v_mul_f32_e32 v6, v6, v136
	v_mul_f32_e32 v22, v22, v137
	v_mul_f32_e32 v7, v7, v138
	v_mul_f32_e32 v23, v23, v139
	v_mul_f32_e32 v4, v4, v64
	v_mul_f32_e32 v20, v20, v65
	v_mul_f32_e32 v5, v5, v66
	v_mul_f32_e32 v21, v21, v67
; __device__ __forceinline__ float bf2f(bf16_t u) { return __uint_as_float(((unsigned)u) << 16); }
; __device__ __forceinline__ bf16_t f2bf(float f) { return (bf16_t)(cvtpk(f, 0.f) & 0xffffu); }
; __device__ __forceinline__ int crow(int r, int hi) { return (r & 3) + 8 * (r >> 2) + 4 * hi; }
; __device__ __forceinline__ float sigmoidf_(float x) { return __builtin_amdgcn_rcpf(1.f + __expf(-x)); }
; __device__ void phase_attn(const Params& p, char* lds) {
;     ...
; #pragma unroll
;     for (int r = 0; r < 16; ++r) {
;       const int orow = crow(r, hi);
; #pragma unroll
;       for (int d0 = 0; d0 < 2; ++d0) {
;         const float gt = bf2f(gin[2 * r + d0]);
;         Gw[(size_t)orow * 1024 + d0 * 32] = f2bf(o[d0][r] * rli[r] * gt * sigmoidf_(gt));
;       }
;     }
	v_mul_f32_e32 v6, v6, v68
	v_mul_f32_e32 v22, v22, v69
	v_mul_f32_e32 v7, v7, v70
	v_mul_f32_e32 v23, v23, v71
	v_cvt_pk_bf16_f32 v4, v4, v4
	v_cvt_pk_bf16_f32 v20, v20, v20
	v_cvt_pk_bf16_f32 v5, v5, v5
	v_cvt_pk_bf16_f32 v21, v21, v21
	v_cvt_pk_bf16_f32 v6, v6, v6
	v_cvt_pk_bf16_f32 v22, v22, v22
	v_cvt_pk_bf16_f32 v7, v7, v7
	v_cvt_pk_bf16_f32 v23, v23, v23
	s_add_u32 s8, s28, 0x4000
	s_addc_u32 s9, s29, 0
	global_store_short v235, v4, s[8:9] offset:0
	global_store_short v235, v20, s[8:9] offset:64
	global_store_short v235, v5, s[8:9] offset:2048
	global_store_short v235, v21, s[8:9] offset:2112
	s_add_u32 s8, s28, 0x5000
	s_addc_u32 s9, s29, 0
	global_store_short v235, v6, s[8:9] offset:0
	global_store_short v235, v22, s[8:9] offset:64
	global_store_short v235, v7, s[8:9] offset:2048
	global_store_short v235, v23, s[8:9] offset:2112
	v_lshlrev_b32_e32 v140, 16, v140
	v_lshlrev_b32_e32 v141, 16, v141
	v_lshlrev_b32_e32 v142, 16, v142
	v_lshlrev_b32_e32 v143, 16, v143
	v_lshlrev_b32_e32 v144, 16, v144
	v_lshlrev_b32_e32 v145, 16, v145
	v_lshlrev_b32_e32 v146, 16, v146
	v_lshlrev_b32_e32 v147, 16, v147
	v_mul_f32_e32 v64, 0xbfb8aa3b, v140
	v_mul_f32_e32 v65, 0xbfb8aa3b, v141
	v_mul_f32_e32 v66, 0xbfb8aa3b, v142
	v_mul_f32_e32 v67, 0xbfb8aa3b, v143
	v_mul_f32_e32 v68, 0xbfb8aa3b, v144
	v_mul_f32_e32 v69, 0xbfb8aa3b, v145
	v_mul_f32_e32 v70, 0xbfb8aa3b, v146
	v_mul_f32_e32 v71, 0xbfb8aa3b, v147
	v_exp_f32_e32 v64, v64
	v_exp_f32_e32 v65, v65
	v_exp_f32_e32 v66, v66
	v_exp_f32_e32 v67, v67
	v_exp_f32_e32 v68, v68
	v_exp_f32_e32 v69, v69
	v_exp_f32_e32 v70, v70
	v_exp_f32_e32 v71, v71
	v_add_f32_e32 v64, 1.0, v64
	v_add_f32_e32 v65, 1.0, v65
	v_add_f32_e32 v66, 1.0, v66
	v_add_f32_e32 v67, 1.0, v67
	v_add_f32_e32 v68, 1.0, v68
	v_add_f32_e32 v69, 1.0, v69
	v_add_f32_e32 v70, 1.0, v70
	v_add_f32_e32 v71, 1.0, v71
	v_rcp_f32_e32 v64, v64
	v_rcp_f32_e32 v65, v65
	v_rcp_f32_e32 v66, v66
	v_rcp_f32_e32 v67, v67
	v_rcp_f32_e32 v68, v68
	v_rcp_f32_e32 v69, v69
	v_rcp_f32_e32 v70, v70
	v_rcp_f32_e32 v71, v71
	v_mul_f32_e32 v8, v8, v140
	v_mul_f32_e32 v24, v24, v141
	v_mul_f32_e32 v9, v9, v142
	v_mul_f32_e32 v25, v25, v143
	v_mul_f32_e32 v10, v10, v144
	v_mul_f32_e32 v26, v26, v145
	v_mul_f32_e32 v11, v11, v146
	v_mul_f32_e32 v27, v27, v147
	v_mul_f32_e32 v8, v8, v64
	v_mul_f32_e32 v24, v24, v65
	v_mul_f32_e32 v9, v9, v66
	v_mul_f32_e32 v25, v25, v67
	v_mul_f32_e32 v10, v10, v68
	v_mul_f32_e32 v26, v26, v69
	v_mul_f32_e32 v11, v11, v70
	v_mul_f32_e32 v27, v27, v71
	v_cvt_pk_bf16_f32 v8, v8, v8
	v_cvt_pk_bf16_f32 v24, v24, v24
	v_cvt_pk_bf16_f32 v9, v9, v9
	v_cvt_pk_bf16_f32 v25, v25, v25
	v_cvt_pk_bf16_f32 v10, v10, v10
	v_cvt_pk_bf16_f32 v26, v26, v26
	v_cvt_pk_bf16_f32 v11, v11, v11
	v_cvt_pk_bf16_f32 v27, v27, v27
	s_add_u32 s8, s28, 0x8000
	s_addc_u32 s9, s29, 0
	global_store_short v235, v8, s[8:9] offset:0
	global_store_short v235, v24, s[8:9] offset:64
	global_store_short v235, v9, s[8:9] offset:2048
	global_store_short v235, v25, s[8:9] offset:2112
	s_add_u32 s8, s28, 0x9000
	s_addc_u32 s9, s29, 0
	global_store_short v235, v10, s[8:9] offset:0
	global_store_short v235, v26, s[8:9] offset:64
	global_store_short v235, v11, s[8:9] offset:2048
	global_store_short v235, v27, s[8:9] offset:2112
	v_lshlrev_b32_e32 v200, 16, v200
	v_lshlrev_b32_e32 v201, 16, v201
	v_lshlrev_b32_e32 v202, 16, v202
	v_lshlrev_b32_e32 v203, 16, v203
	v_lshlrev_b32_e32 v204, 16, v204
	v_lshlrev_b32_e32 v205, 16, v205
	v_lshlrev_b32_e32 v206, 16, v206
	v_lshlrev_b32_e32 v207, 16, v207
	v_mul_f32_e32 v64, 0xbfb8aa3b, v200
	v_mul_f32_e32 v65, 0xbfb8aa3b, v201
	v_mul_f32_e32 v66, 0xbfb8aa3b, v202
	v_mul_f32_e32 v67, 0xbfb8aa3b, v203
	v_mul_f32_e32 v68, 0xbfb8aa3b, v204
	v_mul_f32_e32 v69, 0xbfb8aa3b, v205
	v_mul_f32_e32 v70, 0xbfb8aa3b, v206
	v_mul_f32_e32 v71, 0xbfb8aa3b, v207
	v_exp_f32_e32 v64, v64
	v_exp_f32_e32 v65, v65
	v_exp_f32_e32 v66, v66
	v_exp_f32_e32 v67, v67
	v_exp_f32_e32 v68, v68
	v_exp_f32_e32 v69, v69
	v_exp_f32_e32 v70, v70
	v_exp_f32_e32 v71, v71
	v_add_f32_e32 v64, 1.0, v64
	v_add_f32_e32 v65, 1.0, v65
	v_add_f32_e32 v66, 1.0, v66
	v_add_f32_e32 v67, 1.0, v67
	v_add_f32_e32 v68, 1.0, v68
	v_add_f32_e32 v69, 1.0, v69
	v_add_f32_e32 v70, 1.0, v70
	v_add_f32_e32 v71, 1.0, v71
	v_rcp_f32_e32 v64, v64
	v_rcp_f32_e32 v65, v65
	v_rcp_f32_e32 v66, v66
	v_rcp_f32_e32 v67, v67
	v_rcp_f32_e32 v68, v68
	v_rcp_f32_e32 v69, v69
	v_rcp_f32_e32 v70, v70
	v_rcp_f32_e32 v71, v71
	v_mul_f32_e32 v12, v12, v200
	v_mul_f32_e32 v28, v28, v201
	v_mul_f32_e32 v13, v13, v202
	v_mul_f32_e32 v29, v29, v203
	v_mul_f32_e32 v14, v14, v204
	v_mul_f32_e32 v30, v30, v205
	v_mul_f32_e32 v15, v15, v206
	v_mul_f32_e32 v31, v31, v207
	v_mul_f32_e32 v12, v12, v64
	v_mul_f32_e32 v28, v28, v65
	v_mul_f32_e32 v13, v13, v66
	v_mul_f32_e32 v29, v29, v67
	v_mul_f32_e32 v14, v14, v68
	v_mul_f32_e32 v30, v30, v69
	v_mul_f32_e32 v15, v15, v70
	v_mul_f32_e32 v31, v31, v71
	v_cvt_pk_bf16_f32 v12, v12, v12
	v_cvt_pk_bf16_f32 v28, v28, v28
	v_cvt_pk_bf16_f32 v13, v13, v13
	v_cvt_pk_bf16_f32 v29, v29, v29
	v_cvt_pk_bf16_f32 v14, v14, v14
	v_cvt_pk_bf16_f32 v30, v30, v30
	v_cvt_pk_bf16_f32 v15, v15, v15
	v_cvt_pk_bf16_f32 v31, v31, v31
	s_add_u32 s8, s28, 0xc000
	s_addc_u32 s9, s29, 0
	global_store_short v235, v12, s[8:9] offset:0
	global_store_short v235, v28, s[8:9] offset:64
	global_store_short v235, v13, s[8:9] offset:2048
	global_store_short v235, v29, s[8:9] offset:2112
	s_add_u32 s8, s28, 0xd000
	s_addc_u32 s9, s29, 0
	global_store_short v235, v14, s[8:9] offset:0
	global_store_short v235, v30, s[8:9] offset:64
	global_store_short v235, v15, s[8:9] offset:2048
	global_store_short v235, v31, s[8:9] offset:2112
	s_add_i32 s12, s12, s33
	s_cmpk_lt_u32 s12, 0x200
	s_cbranch_scc1 .Lat_item
	s_branch .Lat_done
